# XCD-local barrier release before phases 3a,3b,4,5,MLP2 (compress/prepass items and extras queues remapped so each batch stays on one XCD group); grid-wide rendezvous kept before phase 1,2 and MLP1 (bu
# speedup vs baseline: 1.0208x; 1.0039x over previous
; DEVI void pull_extras(const Params& p, int l, char* lds, volatile int* nsa_cnt, int max_pulls) {
;   unsigned* q = (unsigned*)(p.ws + OFF_BAR) + 3500 + l;
;   for (int n = 0; n < max_pulls; ++n) {
;     __syncthreads();
;     if (threadIdx.x == 0) nsa_cnt[2] = (int)atomicAdd(q, 2u);
.LBB0_527:
	v_readlane_b32 s0, v242, 43
	v_readlane_b32 s1, v242, 44
	s_mov_b32 s36, s0
	s_ashr_i32 s37, s0, 31
	s_lshl_b64 s[0:1], s[36:37], 2
	v_readlane_b32 s4, v243, 22
	s_add_u32 s0, s4, s0
	v_readlane_b32 s4, v243, 23
	s_addc_u32 s1, s4, s1
	s_mul_i32 s4, s36, 28
	v_readlane_b32 s5, v243, 13
	s_bfe_u32 s5, s5, 0x30001
	s_lshl_b32 s5, s5, 2
	s_add_i32 s4, s4, s5
	s_add_i32 s4, s4, 16
	s_add_u32 s0, s0, s4
	s_addc_u32 s1, s1, 0
	s_mul_hi_i32 s20, s36, 0xc00
	s_mul_i32 s23, s36, 0xc00
	s_mul_hi_i32 s25, s36, 0x7c00
	s_mul_i32 s27, s36, 0x7c00
	s_lshl_b32 s4, s36, 8
	s_mov_b32 s28, s36
	s_lshl_b32 s30, s36, 2
	v_readlane_b32 s36, v244, 35
	s_ashr_i32 s5, s4, 31
	v_readlane_b32 s38, v244, 37
	v_readlane_b32 s40, v244, 39
	v_readlane_b32 s41, v244, 40
	v_readlane_b32 s42, v244, 41
	v_readlane_b32 s43, v244, 42
	v_readlane_b32 s44, v244, 43
	v_readlane_b32 s45, v244, 44
	v_readlane_b32 s46, v244, 45
	v_readlane_b32 s47, v244, 46
	v_readlane_b32 s48, v244, 47
	v_readlane_b32 s49, v244, 48
	v_readlane_b32 s50, v244, 49
	v_readlane_b32 s51, v244, 50
	v_readlane_b32 s37, v244, 36
	v_readlane_b32 s39, v244, 38
	s_add_u32 s38, s36, s23
	v_readlane_b32 s40, v244, 19
	s_addc_u32 s39, s37, s20
	v_readlane_b32 s48, v244, 27
	v_writelane_b32 v242, s28, 43
	v_readlane_b32 s41, v244, 20
	v_readlane_b32 s49, v244, 28
	s_add_u32 s40, s48, s27
	v_writelane_b32 v242, s29, 44
	v_readlane_b32 s42, v244, 21
	v_readlane_b32 s52, v244, 31
	s_addc_u32 s41, s49, s25
	s_lshl_b64 s[28:29], s[4:5], 2
	v_readlane_b32 s43, v244, 22
	v_readlane_b32 s53, v244, 32
	s_add_u32 s42, s52, s28
	v_readlane_b32 s44, v244, 23
	v_readlane_b32 s54, v244, 33
	s_addc_u32 s43, s53, s29
	v_readlane_b32 s45, v244, 24
	v_readlane_b32 s50, v244, 29
	v_readlane_b32 s51, v244, 30
	v_readlane_b32 s55, v244, 34
	s_add_u32 s44, s54, s28
	s_addc_u32 s45, s55, s29
	v_readlane_b32 s48, v244, 3
	v_readlane_b32 s46, v244, 25
	v_readlane_b32 s54, v244, 9
	v_readlane_b32 s47, v244, 26
	v_readlane_b32 s55, v244, 10
	s_add_u32 s46, s54, s28
	v_readlane_b32 s56, v244, 11
	s_addc_u32 s47, s55, s29
	v_readlane_b32 s49, v244, 4
	v_readlane_b32 s50, v244, 5
	v_readlane_b32 s51, v244, 6
	v_readlane_b32 s57, v244, 12
	v_readlane_b32 s62, v244, 17
	v_readlane_b32 s63, v244, 18
	s_add_u32 s48, s56, s28
	s_addc_u32 s49, s57, s29
	s_add_i32 s5, s26, 0x7c00
	s_add_i32 s62, s26, 0x4400
	s_mov_b32 s63, 0
	s_mov_b64 s[50:51], 0
	s_movk_i32 s11, 0x500
	s_movk_i32 s23, 0x1000
	v_readlane_b32 s52, v244, 7
	v_readlane_b32 s53, v244, 8
	v_readlane_b32 s58, v244, 13
	v_readlane_b32 s59, v244, 14
	v_readlane_b32 s60, v244, 15
	v_readlane_b32 s61, v244, 16
	s_branch .LBB0_529

; DEVI int vhalf() { int t = threadIdx.x >> 8; t = __builtin_amdgcn_readfirstlane(t); return t; }
; DEVI void pull_extras(const Params& p, int l, char* lds, volatile int* nsa_cnt, int max_pulls) {
;     ...
;     if (threadIdx.x == 0) nsa_cnt[2] = (int)atomicAdd(q, 2u);
;     __syncthreads();
;     const int base = nsa_cnt[2];
;     if (base >= P3B_EXTRA) break;
;     int i = base + vhalf();
;     if (i < P3_GMLP) { gmlp_item(p, l, i, lds); continue; }
;     i -= P3_GMLP;
;     if (i < P3_CONF) { conf_item(p, l, i, lds); continue; }
;     i -= P3_CONF;
;     sconv_item(p, l, i);
.LBB0_532:
	s_or_b64 exec, exec, s[52:53]
	s_mov_b64 s[28:29], src_shared_base
	s_waitcnt vmcnt(0)
	v_readfirstlane_b32 s20, v2
	v_readlane_b32 vcc_hi, v243, 13
	s_bfe_u32 vcc_hi, vcc_hi, 0x30001
	s_lshl_b32 vcc_lo, vcc_hi, 6
	s_add_i32 vcc_lo, vcc_lo, s20
	s_cmp_lt_u32 s20, 64
	s_cbranch_scc1 .Lq3b_done
	s_addk_i32 vcc_lo, 448
	s_cmp_lt_u32 s20, 0x80
	s_cbranch_scc1 .Lq3b_done
	s_lshl_b32 vcc_lo, vcc_hi, 5
	s_add_i32 vcc_lo, vcc_lo, s20
	s_addk_i32 vcc_lo, 896
	s_cmp_lt_u32 s20, 0xa0
	s_cbranch_scc1 .Lq3b_done
	s_movk_i32 vcc_lo, 0x500
.Lq3b_done:
	s_mov_b32 s20, vcc_lo
	v_mov_b32_e32 v183, s29
	s_nop 0
	v_lshl_add_u32 v0, v0, 1, s20
	flat_store_dword v[182:183], v0 sc0 sc1
	s_waitcnt vmcnt(0)

; DEVI int get_tid() { int t = threadIdx.x & 255; asm volatile("" : "+v"(t)); return t; }
; DEVI void compress_item(const Params& p, int l, int ci, char* lds) {
;     ...
;   const int kv = ci >> 4, bh = ci & 15, b = bh >> 1, h = bh & 1;
;   const int lane = get_tid() & 63, wid = get_tid() >> 6, wm = wid >> 1, wn = wid & 1, fr = lane & 15, fq = lane >> 4;
;   bfu* chid = (bfu*)(p.ws + OFF_CHID) + (long)ci * 128 * 128;
; DEVI void phase3a(const Params& p, int l, char* lds, bool rep, volatile int* nsa_cnt) {
;     ...
;   const int wg = (int)blockIdx.x, nwg = (int)gridDim.x;
;   if (wg < P3_CMP) {
;     for (int i = wg; i < P3_CMP; i += nwg) compress_item(p, l, i, lds);
.LBB0_601:
	s_and_b64 vcc, exec, s[0:1]
	s_cbranch_vccz .LBB0_670
	v_readlane_b32 s0, v244, 57
	v_readlane_b32 s1, v244, 58
	s_load_dword s27, s[0:1], 0x0
	v_readlane_b32 s0, v243, 24
	v_readlane_b32 s1, v243, 25
	v_readfirstlane_b32 s29, v220
	s_andn2_b64 vcc, exec, s[0:1]
	s_mov_b64 s[0:1], -1
	s_cbranch_vccnz .LBB0_657
	v_readlane_b32 s0, v242, 43
	v_readlane_b32 s1, v242, 44
	s_mul_i32 s0, s0, 3
	s_ashr_i32 s1, s0, 31
	s_lshl_b64 s[0:1], s[0:1], 8
	v_readlane_b32 s36, v244, 19
	v_readlane_b32 s37, v244, 20
	v_readlane_b32 s42, v244, 25
	v_readlane_b32 s45, v244, 28
	s_add_u32 s4, s36, s0
	v_readlane_b32 s0, v244, 0
	s_addc_u32 s5, s37, s1
	s_waitcnt lgkmcnt(0)
	s_lshl_b32 s52, s27, 13
	v_readlane_b32 s53, v242, 36
	s_and_b32 s42, s0, 7
	s_lshl_b32 s42, s42, 1
	s_bfe_u32 s28, s0, 0x10003
	s_or_b32 s42, s42, s28
	s_bfe_u32 s28, s0, 0x10004
	s_lshl_b32 s28, s28, 4
	s_or_b32 s42, s42, s28
	s_lshl_b32 s53, s42, 13
	v_readlane_b32 s28, v243, 26
	v_readlane_b32 s45, v243, 27
	v_readlane_b32 s38, v244, 21
	v_readlane_b32 s39, v244, 22
	v_readlane_b32 s40, v244, 23
	v_readlane_b32 s41, v244, 24
	v_readlane_b32 s43, v244, 26
	v_readlane_b32 s44, v244, 27
	v_readlane_b32 s46, v244, 29
	v_readlane_b32 s47, v244, 30
	v_readlane_b32 s48, v244, 31
	v_readlane_b32 s49, v244, 32
	v_readlane_b32 s50, v244, 33
	v_readlane_b32 s51, v244, 34
	s_branch .LBB0_606

; DEVI void phase3a(const Params& p, int l, char* lds, bool rep, volatile int* nsa_cnt) {
;     ...
;   const bool split = (nwg > 2 * P3_CMP);
;   const int first = split ? v - 2 * P3_CMP : v, step = split ? nv - 2 * P3_CMP : nv;
;   for (int item = first; item < P3_PRE; item += step) prepass_item(p, l, item, lds);
.LBB0_657:
	s_and_b64 vcc, exec, s[0:1]
	s_cbranch_vccz .LBB0_670
	s_lshr_b32 s0, s29, 8
	v_readlane_b32 s1, v243, 13
	s_add_i32 s20, s0, s1
	s_waitcnt lgkmcnt(0)
	s_cmp_gt_i32 s27, 64
	s_cselect_b64 s[0:1], -1, 0
	s_lshr_b32 s23, s20, 4
	s_lshl_b32 s23, s23, 1
	s_and_b32 s25, s20, 1
	s_add_i32 s23, s23, s25
	s_add_i32 s23, s23, -8
	s_bfe_u32 s25, s20, 0x30001
	s_lshl_b32 s25, s25, 5
	s_add_i32 s25, s25, s23
	s_cmp_lt_u32 s23, 32
	s_cselect_b32 s23, s25, 0x100
	s_cmpk_lt_i32 s27, 0x41
	s_cselect_b64 s[4:5], -1, 0
	s_and_b64 s[28:29], s[4:5], exec
	s_cselect_b32 s20, s20, s23
	s_cmpk_gt_i32 s20, 0xff
	s_movk_i32 s21, 0x80
	s_movk_i32 s38, 0x210
	s_cbranch_scc1 .LBB0_661
	s_lshl_b32 s23, s27, 1
	s_sub_i32 s25, s23, 64
	s_and_b64 s[4:5], s[4:5], exec
	s_cselect_b32 s23, s23, s25
	s_lshl_b32 s25, s20, 6
	s_lshl_b32 s27, s23, 6

; DEVI int vhalf() { int t = threadIdx.x >> 8; t = __builtin_amdgcn_readfirstlane(t); return t; }
; DEVI void pull_extras(const Params& p, int l, char* lds, volatile int* nsa_cnt, int max_pulls) {
;   unsigned* q = (unsigned*)(p.ws + OFF_BAR) + 3500 + l;
;   for (int n = 0; n < max_pulls; ++n) {
;     __syncthreads();
;     if (threadIdx.x == 0) nsa_cnt[2] = (int)atomicAdd(q, 2u);
;     __syncthreads();
;     const int base = nsa_cnt[2];
;     if (base >= P3B_EXTRA) break;
;     int i = base + vhalf();
;     if (i < P3_GMLP) { gmlp_item(p, l, i, lds); continue; }
;     i -= P3_GMLP;
;     if (i < P3_CONF) { conf_item(p, l, i, lds); continue; }
;     i -= P3_CONF;
;     sconv_item(p, l, i);
.LBB0_661:
	s_and_b64 vcc, exec, s[0:1]
	s_cbranch_vccz .LBB0_670
	v_readlane_b32 s0, v242, 43
	v_readlane_b32 s1, v242, 44
	s_ashr_i32 s1, s0, 31
	v_writelane_b32 v242, s0, 43
	s_waitcnt vmcnt(0)
	s_barrier
	v_writelane_b32 v242, s1, 44
	s_mov_b64 s[0:1], exec
	v_readlane_b32 s4, v242, 37
	v_readlane_b32 s5, v242, 38
	s_and_b64 s[4:5], s[0:1], s[4:5]
	s_mov_b64 exec, s[4:5]
	s_cbranch_execz .LBB0_666
	s_mov_b64 s[36:37], exec
	v_mbcnt_lo_u32_b32 v0, s36, 0
	v_mbcnt_hi_u32_b32 v0, s37, v0
	v_cmp_eq_u32_e32 vcc, 0, v0
	s_and_saveexec_b64 s[4:5], vcc
	s_cbranch_execz .LBB0_665
	v_readlane_b32 s20, v242, 43
	v_readlane_b32 s21, v242, 44
	s_lshl_b64 s[28:29], s[20:21], 2
	v_readlane_b32 s11, v243, 22
	s_add_u32 s28, s11, s28
	v_readlane_b32 s11, v243, 23
	s_addc_u32 s29, s11, s29
	s_mul_i32 s20, s20, 28
	v_readlane_b32 s11, v243, 13
	s_bfe_u32 s11, s11, 0x30001
	s_lshl_b32 s11, s11, 2
	s_add_i32 s20, s20, s11
	s_add_i32 s20, s20, 16
	s_add_u32 s28, s28, s20
	s_addc_u32 s29, s29, 0
	s_bcnt1_i32_b64 s20, s[36:37]
	s_lshl_b32 s20, s20, 1
	v_mov_b32_e32 v2, s20
	global_atomic_add v2, v1, v2, s[28:29] sc0
	s_movk_i32 s11, 0x500
.LBB0_665:
	s_or_b64 exec, exec, s[4:5]
	s_mov_b64 s[4:5], src_shared_base
	s_waitcnt vmcnt(0)
	v_readfirstlane_b32 s4, v2
	v_readlane_b32 s20, v243, 13
	s_bfe_u32 s20, s20, 0x30001
	s_lshl_b32 vcc_lo, s20, 6
	s_add_i32 vcc_lo, vcc_lo, s4
	s_cmp_lt_u32 s4, 64
	s_cbranch_scc1 .Lq3a_done
	s_addk_i32 vcc_lo, 448
	s_cmp_lt_u32 s4, 0x80
	s_cbranch_scc1 .Lq3a_done
	s_lshl_b32 vcc_lo, s20, 5
	s_add_i32 vcc_lo, vcc_lo, s4
	s_addk_i32 vcc_lo, 896
	s_cmp_lt_u32 s4, 0xa0
	s_cbranch_scc1 .Lq3a_done
	s_movk_i32 vcc_lo, 0x500
.Lq3a_done:
	s_mov_b32 s4, vcc_lo
	v_mov_b32_e32 v183, s5
	s_nop 0
	v_lshl_add_u32 v0, v0, 1, s4
	flat_store_dword v[182:183], v0 sc0 sc1
	s_waitcnt vmcnt(0)

; DEVI unsigned xb_ld(unsigned* p) { return __hip_atomic_load(p, __ATOMIC_RELAXED, __HIP_MEMORY_SCOPE_AGENT); }
; DEVI unsigned xb_add(unsigned* p, unsigned v) { return __hip_atomic_fetch_add(p, v, __ATOMIC_RELAXED, __HIP_MEMORY_SCOPE_AGENT); }
; #define XB_SPIN(cond, bar) do { unsigned _sp = 0; while (cond) { __builtin_amdgcn_s_sleep(1); \
;     if ((++_sp & 255u) == 0u) { if (xb_ld(&(bar)[XB_TMO])) break; if (_sp > XB_SPIN_CAP) { atomicAdd(&(bar)[XB_TMO], 1u); break; } } } } while (0)
; DEVI void xcd_barrier(const XcdBarrier& b) {
;   asm volatile("s_waitcnt vmcnt(0)" ::: "memory");
;   __syncthreads();
;   if (threadIdx.x == 0) {
;     unsigned* bar = b.bar;
;     __builtin_amdgcn_s_waitcnt(0);
;     unsigned nloc = b.st[0], nx = b.st[1];
;     if (nloc == 0u) { xcd_barrier_complete(bar, b.x, nloc, nx); b.st[0] = nloc; b.st[1] = nx; }
;     const unsigned old = xb_add(&bar[XB_XSUB(b.x)], 1u);
;     const unsigned gen = old / nloc;
;     if (old + 1u == (gen + 1u) * nloc) {
;       __builtin_amdgcn_fence(__ATOMIC_RELEASE, "agent");
;       asm volatile("s_waitcnt vmcnt(0)" ::: "memory");
;       const unsigned og = xb_add(&bar[XB_TOP], 1u);
;       const unsigned tg = og / nx;
;       if (og + 1u == (tg + 1u) * nx) xb_add(&bar[XB_TOPGEN], 1u);
;       else XB_SPIN(xb_ld(&bar[XB_TOPGEN]) == tg, bar);
.LBB0_962:
	s_and_b32 s20, s92, 7
	s_cmp_lt_u32 s20, 2
	s_cbranch_scc1 .Lxb_global
	s_cmp_eq_u32 s20, 6
	s_cbranch_scc1 .Lxb_global
	v_readfirstlane_b32 s20, v246
	s_bcnt1_i32_b32 s20, s20
	s_cmp_lg_u32 s20, 1
	s_cbranch_scc1 .Lxb_global
	v_readfirstlane_b32 s20, v247
	s_bcnt1_i32_b32 s20, s20
	s_cmp_lg_u32 s20, 1
	s_cbranch_scc1 .Lxb_global
	v_readfirstlane_b32 s20, v248
	s_bcnt1_i32_b32 s20, s20
	s_cmp_lg_u32 s20, 1
	s_cbranch_scc1 .Lxb_global
	v_readfirstlane_b32 s20, v249
	s_bcnt1_i32_b32 s20, s20
	s_cmp_lg_u32 s20, 1
	s_cbranch_scc1 .Lxb_global
	v_readfirstlane_b32 s20, v250
	s_bcnt1_i32_b32 s20, s20
	s_cmp_lg_u32 s20, 1
	s_cbranch_scc1 .Lxb_global
	v_readfirstlane_b32 s20, v251
	s_bcnt1_i32_b32 s20, s20
	s_cmp_lg_u32 s20, 1
	s_cbranch_scc1 .Lxb_global
	v_readfirstlane_b32 s20, v252
	s_bcnt1_i32_b32 s20, s20
	s_cmp_lg_u32 s20, 1
	s_cbranch_scc1 .Lxb_global
	v_readfirstlane_b32 s20, v253
	s_bcnt1_i32_b32 s20, s20
	s_cmp_lg_u32 s20, 1
	s_cbranch_scc1 .Lxb_global
	s_branch .Lxb_local_leader
